# NSA top-16 block selection: 64-step readlane ranking loop replaced by 32-step bitwise search for the 16th largest key + mbcnt tie-break (identical masks)
# speedup vs baseline: 1.0514x; 1.0214x over previous
; __device__ __forceinline__ void nsa_unit(const Ctx& c, int l, int b, int n, int qt) {
;     ...
;         for (int i = 0; i < 8; ++i) { const int q = wid * 8 + i;
;             const float iv = ((imp[(size_t)(0 * 64 + q) * 65 + lane] + imp[(size_t)(1 * 64 + q) * 65 + lane]) + imp[(size_t)(2 * 64 + q) * 65 + lane]) + imp[(size_t)(3 * 64 + q) * 65 + lane];
;             const bool excl = lane > qt; const bool forced = (lane == 0) || (lane == qt) || (lane + 1 == qt);
;             const float sc = excl ? -__builtin_inff() : (forced ? __builtin_inff() : iv);
;             int cnt = 0; const int sci = __float_as_int(sc);
; #pragma unroll 8
;             for (int k = 0; k < 64; ++k) { const float si = __int_as_float(__builtin_amdgcn_readlane(sci, k)); cnt += ((si > sc) || (si == sc && k < lane)) ? 1 : 0; }
;             const unsigned long long mk = __ballot(!excl && cnt < 16);
;             if (lane == 0) maskb[q] = mk; }
.LBB0_1318:
	s_or_b32 s20, s19, s1
	s_mul_i32 s6, s20, 0x104
	s_add_i32 s6, s6, 0
	v_lshlrev_b32_e32 v0, 2, v247
	v_add_u32_e32 v2, s6, v0
	ds_read2st64_b32 v[2:3], v2 offset0:132 offset1:197
	s_add_i32 s7, s6, 0x8400
	v_add_u32_e32 v0, s7, v0
	s_mov_b32 s8, 0
	s_waitcnt lgkmcnt(0)
	v_add_f32_e32 v4, v2, v3
	ds_read2st64_b32 v[2:3], v0 offset0:130 offset1:195
	s_waitcnt lgkmcnt(0)
	v_add_f32_e32 v0, v4, v2
	v_add_f32_e32 v0, v0, v3
	v_cndmask_b32_e64 v0, v0, v222, s[4:5]
	v_cndmask_b32_e32 v0, v224, v0, vcc
	v_ashrrev_i32_e32 v2, 31, v0
	v_or_b32_e32 v2, 0x80000000, v2
	v_xor_b32_e32 v2, v0, v2
	s_mov_b32 s9, 0
	s_or_b32 s24, s9, 0x80000000
	v_cmp_ge_u32_e64 s[36:37], v2, s24
	s_bcnt1_i32_b64 s25, s[36:37]
	s_cmp_gt_u32 s25, 15
	s_cselect_b32 s9, s24, s9
	s_or_b32 s24, s9, 0x40000000
	v_cmp_ge_u32_e64 s[36:37], v2, s24
	s_bcnt1_i32_b64 s25, s[36:37]
	s_cmp_gt_u32 s25, 15
	s_cselect_b32 s9, s24, s9
	s_or_b32 s24, s9, 0x20000000
	v_cmp_ge_u32_e64 s[36:37], v2, s24
	s_bcnt1_i32_b64 s25, s[36:37]
	s_cmp_gt_u32 s25, 15
	s_cselect_b32 s9, s24, s9
	s_or_b32 s24, s9, 0x10000000
	v_cmp_ge_u32_e64 s[36:37], v2, s24
	s_bcnt1_i32_b64 s25, s[36:37]
	s_cmp_gt_u32 s25, 15
	s_cselect_b32 s9, s24, s9
	s_or_b32 s24, s9, 0x8000000
	v_cmp_ge_u32_e64 s[36:37], v2, s24
	s_bcnt1_i32_b64 s25, s[36:37]
	s_cmp_gt_u32 s25, 15
	s_cselect_b32 s9, s24, s9
	s_or_b32 s24, s9, 0x4000000
	v_cmp_ge_u32_e64 s[36:37], v2, s24
	s_bcnt1_i32_b64 s25, s[36:37]
	s_cmp_gt_u32 s25, 15
	s_cselect_b32 s9, s24, s9
	s_or_b32 s24, s9, 0x2000000
	v_cmp_ge_u32_e64 s[36:37], v2, s24
	s_bcnt1_i32_b64 s25, s[36:37]
	s_cmp_gt_u32 s25, 15
	s_cselect_b32 s9, s24, s9
	s_or_b32 s24, s9, 0x1000000
	v_cmp_ge_u32_e64 s[36:37], v2, s24
	s_bcnt1_i32_b64 s25, s[36:37]
	s_cmp_gt_u32 s25, 15
	s_cselect_b32 s9, s24, s9
	s_or_b32 s24, s9, 0x800000
	v_cmp_ge_u32_e64 s[36:37], v2, s24
	s_bcnt1_i32_b64 s25, s[36:37]
	s_cmp_gt_u32 s25, 15
	s_cselect_b32 s9, s24, s9
	s_or_b32 s24, s9, 0x400000
	v_cmp_ge_u32_e64 s[36:37], v2, s24
	s_bcnt1_i32_b64 s25, s[36:37]
	s_cmp_gt_u32 s25, 15
	s_cselect_b32 s9, s24, s9
	s_or_b32 s24, s9, 0x200000
	v_cmp_ge_u32_e64 s[36:37], v2, s24
	s_bcnt1_i32_b64 s25, s[36:37]
	s_cmp_gt_u32 s25, 15
	s_cselect_b32 s9, s24, s9
	s_or_b32 s24, s9, 0x100000
	v_cmp_ge_u32_e64 s[36:37], v2, s24
	s_bcnt1_i32_b64 s25, s[36:37]
	s_cmp_gt_u32 s25, 15
	s_cselect_b32 s9, s24, s9
	s_or_b32 s24, s9, 0x80000
	v_cmp_ge_u32_e64 s[36:37], v2, s24
	s_bcnt1_i32_b64 s25, s[36:37]
	s_cmp_gt_u32 s25, 15
	s_cselect_b32 s9, s24, s9
	s_or_b32 s24, s9, 0x40000
	v_cmp_ge_u32_e64 s[36:37], v2, s24
	s_bcnt1_i32_b64 s25, s[36:37]
	s_cmp_gt_u32 s25, 15
	s_cselect_b32 s9, s24, s9
	s_or_b32 s24, s9, 0x20000
	v_cmp_ge_u32_e64 s[36:37], v2, s24
	s_bcnt1_i32_b64 s25, s[36:37]
	s_cmp_gt_u32 s25, 15
	s_cselect_b32 s9, s24, s9
	s_or_b32 s24, s9, 0x10000
	v_cmp_ge_u32_e64 s[36:37], v2, s24
	s_bcnt1_i32_b64 s25, s[36:37]
	s_cmp_gt_u32 s25, 15
	s_cselect_b32 s9, s24, s9
	s_or_b32 s24, s9, 0x8000
	v_cmp_ge_u32_e64 s[36:37], v2, s24
	s_bcnt1_i32_b64 s25, s[36:37]
	s_cmp_gt_u32 s25, 15
	s_cselect_b32 s9, s24, s9
	s_or_b32 s24, s9, 0x4000
	v_cmp_ge_u32_e64 s[36:37], v2, s24
	s_bcnt1_i32_b64 s25, s[36:37]
	s_cmp_gt_u32 s25, 15
	s_cselect_b32 s9, s24, s9
	s_or_b32 s24, s9, 0x2000
	v_cmp_ge_u32_e64 s[36:37], v2, s24
	s_bcnt1_i32_b64 s25, s[36:37]
	s_cmp_gt_u32 s25, 15
	s_cselect_b32 s9, s24, s9
	s_or_b32 s24, s9, 0x1000
	v_cmp_ge_u32_e64 s[36:37], v2, s24
	s_bcnt1_i32_b64 s25, s[36:37]
	s_cmp_gt_u32 s25, 15
	s_cselect_b32 s9, s24, s9
	s_or_b32 s24, s9, 0x800
	v_cmp_ge_u32_e64 s[36:37], v2, s24
	s_bcnt1_i32_b64 s25, s[36:37]
	s_cmp_gt_u32 s25, 15
	s_cselect_b32 s9, s24, s9
	s_or_b32 s24, s9, 0x400
	v_cmp_ge_u32_e64 s[36:37], v2, s24
	s_bcnt1_i32_b64 s25, s[36:37]
	s_cmp_gt_u32 s25, 15
	s_cselect_b32 s9, s24, s9
	s_or_b32 s24, s9, 0x200
	v_cmp_ge_u32_e64 s[36:37], v2, s24
	s_bcnt1_i32_b64 s25, s[36:37]
	s_cmp_gt_u32 s25, 15
	s_cselect_b32 s9, s24, s9
	s_or_b32 s24, s9, 0x100
	v_cmp_ge_u32_e64 s[36:37], v2, s24
	s_bcnt1_i32_b64 s25, s[36:37]
	s_cmp_gt_u32 s25, 15
	s_cselect_b32 s9, s24, s9
	s_or_b32 s24, s9, 0x80
	v_cmp_ge_u32_e64 s[36:37], v2, s24
	s_bcnt1_i32_b64 s25, s[36:37]
	s_cmp_gt_u32 s25, 15
	s_cselect_b32 s9, s24, s9
	s_or_b32 s24, s9, 0x40
	v_cmp_ge_u32_e64 s[36:37], v2, s24
	s_bcnt1_i32_b64 s25, s[36:37]
	s_cmp_gt_u32 s25, 15
	s_cselect_b32 s9, s24, s9
	s_or_b32 s24, s9, 0x20
	v_cmp_ge_u32_e64 s[36:37], v2, s24
	s_bcnt1_i32_b64 s25, s[36:37]
	s_cmp_gt_u32 s25, 15
	s_cselect_b32 s9, s24, s9
	s_or_b32 s24, s9, 0x10
	v_cmp_ge_u32_e64 s[36:37], v2, s24
	s_bcnt1_i32_b64 s25, s[36:37]
	s_cmp_gt_u32 s25, 15
	s_cselect_b32 s9, s24, s9
	s_or_b32 s24, s9, 0x8
	v_cmp_ge_u32_e64 s[36:37], v2, s24
	s_bcnt1_i32_b64 s25, s[36:37]
	s_cmp_gt_u32 s25, 15
	s_cselect_b32 s9, s24, s9
	s_or_b32 s24, s9, 0x4
	v_cmp_ge_u32_e64 s[36:37], v2, s24
	s_bcnt1_i32_b64 s25, s[36:37]
	s_cmp_gt_u32 s25, 15
	s_cselect_b32 s9, s24, s9
	s_or_b32 s24, s9, 0x2
	v_cmp_ge_u32_e64 s[36:37], v2, s24
	s_bcnt1_i32_b64 s25, s[36:37]
	s_cmp_gt_u32 s25, 15
	s_cselect_b32 s9, s24, s9
	s_or_b32 s24, s9, 0x1
	v_cmp_ge_u32_e64 s[36:37], v2, s24
	s_bcnt1_i32_b64 s25, s[36:37]
	s_cmp_gt_u32 s25, 15
	s_cselect_b32 s9, s24, s9
	v_cmp_gt_u32_e64 s[36:37], v2, s9
	v_cmp_eq_u32_e64 s[42:43], v2, s9
	s_bcnt1_i32_b64 s25, s[36:37]
	s_sub_i32 s25, 16, s25
	v_mbcnt_lo_u32_b32 v3, s42, 0
	v_mbcnt_hi_u32_b32 v3, s43, v3
	v_cmp_gt_i32_e64 s[6:7], s25, v3
	s_and_b64 s[6:7], s[6:7], s[42:43]
	s_or_b64 s[6:7], s[6:7], s[36:37]
	s_and_b64 s[8:9], s[6:7], vcc
	s_and_saveexec_b64 s[6:7], s[2:3]
	s_cbranch_execz .LBB0_1317
	s_lshl_b32 s20, s20, 3
	s_add_i32 s20, s20, 0
	s_add_i32 s20, s20, 0x18800
	v_mov_b32_e32 v0, s20
	v_mov_b64_e32 v[2:3], s[8:9]
	ds_write_b64 v0, v[2:3]
	s_branch .LBB0_1317
